# attention A loop: lane^32 max exchange via v_permlane32_swap instead of ds_bpermute round trip
# speedup vs baseline: 1.0050x; 1.0050x over previous
; __device__ __forceinline__ float ex2(float v) { return __builtin_amdgcn_exp2f(v); }
; #define MFMA32(a, b, c) __builtin_amdgcn_mfma_f32_32x32x16_bf16((a), (b), (c), 0, 0, 0)
; __device__ __forceinline__ void tileA_post(AState& S, f32x16& s, const bf16x8 (&vf)[4], const LAS float* tb2, int kbase, int q0, int ql, int hi) {
;     ...
;     float mx = s[0];
; #pragma unroll
;     for (int r = 1; r < 16; ++r) mx = fmaxf(mx, s[r]);
;     mx = fmaxf(mx, __shfl_xor(mx, 32));
;     const float mnew = fmaxf(S.mrun, mx), alpha = ex2(S.mrun - mnew);
;     S.mrun = mnew;
;     float rs = 0.f;
; #pragma unroll
;     for (int r = 0; r < 16; ++r) { s[r] = ex2(s[r] - mnew); rs += s[r]; }
;     S.l = S.l * alpha + rs;
; #pragma unroll
;     for (int r = 0; r < 16; ++r) { S.o0[r] *= alpha; S.o1[r] *= alpha; }
;     const bf16x8 p0 = pack8(s, 0), p1 = pack8(s, 8);
;     S.o0 = MFMA32(vf[0], p0, S.o0); S.o0 = MFMA32(vf[1], p1, S.o0);
;     S.o1 = MFMA32(vf[2], p0, S.o1); S.o1 = MFMA32(vf[3], p1, S.o1);
; __device__ __forceinline__ void attnA_wave(LAS unsigned char* st, const LAS float* tb2, const bf16* QKV, bf16* O, float* sso, int b, int h, int qblk, int lane) {
;     ...
;         tileA_post(S, sc, vfc, tb2, 32 * (t0 + i), q0, ql, hi);
;         if (more) {
;             ATD_VFRAGS(vfc, A, st, (i + 1) & 1);
;             if (i + 3 < n) ATD_DMA(A, st, t0 + i + 3, (i + 1) & 1);
.LBB0_313:
	s_nop 0
	v_max_f32_e32 v65, v49, v49
	v_max_f32_e32 v66, v48, v48
	v_max_f32_e32 v65, v66, v65
	v_max3_f32 v65, v65, v50, v51
	v_max3_f32 v65, v65, v52, v53
	v_max3_f32 v65, v65, v54, v55
	v_max3_f32 v65, v65, v56, v57
	v_max3_f32 v65, v65, v58, v59
	v_cmp_lt_i32_e32 vcc, v208, v207
	v_max3_f32 v65, v65, v60, v61
	v_max3_f32 v65, v65, v62, v63
	v_mov_b32_e32 v66, v65
	s_nop 1
	v_permlane32_swap_b32_e32 v65, v66
	s_andn2_b64 vcc, exec, s[78:79]
	s_waitcnt lgkmcnt(0)
	v_max3_f32 v186, v64, v65, v66
	v_sub_f32_e32 v48, v48, v186
	v_sub_f32_e32 v80, v64, v186
	v_exp_f32_e32 v64, v48
	v_sub_f32_e32 v48, v49, v186
	v_exp_f32_e32 v65, v48
	v_sub_f32_e32 v48, v50, v186
	v_exp_f32_e32 v66, v48
	v_sub_f32_e32 v48, v51, v186
	v_exp_f32_e32 v67, v48
	v_sub_f32_e32 v48, v52, v186
	v_exp_f32_e32 v68, v48
	v_sub_f32_e32 v48, v53, v186
	v_exp_f32_e32 v69, v48
	v_sub_f32_e32 v48, v54, v186
	v_exp_f32_e32 v70, v48
	v_sub_f32_e32 v48, v55, v186
	v_exp_f32_e32 v71, v48
	v_sub_f32_e32 v48, v56, v186
	v_exp_f32_e32 v72, v48
	v_sub_f32_e32 v48, v57, v186
	v_exp_f32_e32 v73, v48
	v_sub_f32_e32 v48, v58, v186
	v_exp_f32_e32 v74, v48
	v_sub_f32_e32 v48, v59, v186
	v_exp_f32_e32 v75, v48
	v_sub_f32_e32 v48, v60, v186
	v_exp_f32_e32 v80, v80
	v_exp_f32_e32 v76, v48
	v_sub_f32_e32 v48, v61, v186
	v_exp_f32_e32 v77, v48
	v_sub_f32_e32 v48, v62, v186
	v_exp_f32_e32 v78, v48
	v_sub_f32_e32 v48, v63, v186
	v_exp_f32_e32 v79, v48
	v_pk_mul_f32 v[14:15], v[14:15], v[80:81] op_sel_hi:[1,0]
	v_pk_mul_f32 v[12:13], v[12:13], v[80:81] op_sel_hi:[1,0]
	v_pk_mul_f32 v[10:11], v[10:11], v[80:81] op_sel_hi:[1,0]
	v_pk_mul_f32 v[8:9], v[8:9], v[80:81] op_sel_hi:[1,0]
	v_pk_mul_f32 v[6:7], v[6:7], v[80:81] op_sel_hi:[1,0]
	v_pk_mul_f32 v[4:5], v[4:5], v[80:81] op_sel_hi:[1,0]
	v_pk_mul_f32 v[2:3], v[2:3], v[80:81] op_sel_hi:[1,0]
	v_pk_mul_f32 v[0:1], v[0:1], v[80:81] op_sel_hi:[1,0]
	v_pk_mul_f32 v[30:31], v[30:31], v[80:81] op_sel_hi:[1,0]
	v_pk_mul_f32 v[28:29], v[28:29], v[80:81] op_sel_hi:[1,0]
	v_pk_mul_f32 v[26:27], v[26:27], v[80:81] op_sel_hi:[1,0]
	v_pk_mul_f32 v[24:25], v[24:25], v[80:81] op_sel_hi:[1,0]
	v_pk_mul_f32 v[22:23], v[22:23], v[80:81] op_sel_hi:[1,0]
	v_pk_mul_f32 v[20:21], v[20:21], v[80:81] op_sel_hi:[1,0]
	v_pk_mul_f32 v[18:19], v[18:19], v[80:81] op_sel_hi:[1,0]
	v_pk_mul_f32 v[16:17], v[16:17], v[80:81] op_sel_hi:[1,0]
	v_cvt_pk_bf16_f32 v48, v64, v65
	v_cvt_pk_bf16_f32 v49, v66, v67
	v_cvt_pk_bf16_f32 v50, v68, v69
	v_cvt_pk_bf16_f32 v51, v70, v71
	v_cvt_pk_bf16_f32 v52, v72, v73
	v_cvt_pk_bf16_f32 v53, v74, v75
	v_mfma_f32_32x32x16_bf16 v[0:15], v[98:101], v[48:51], v[0:15]
	v_cvt_pk_bf16_f32 v54, v76, v77
	v_cvt_pk_bf16_f32 v55, v78, v79
	v_mfma_f32_32x32x16_bf16 v[16:31], v[106:109], v[48:51], v[16:31]
	s_nop 0
	v_mfma_f32_32x32x16_bf16 v[0:15], v[102:105], v[52:55], v[0:15]
	v_mfma_f32_32x32x16_bf16 v[16:31], v[110:113], v[52:55], v[16:31]
	s_cbranch_vccnz .LBB0_323
	s_and_b32 s78, s90, 0x2000
	s_add_i32 s78, s33, s78
	v_add_u32_e32 v48, s78, v152
	v_add_u32_e32 v49, s78, v153
	s_waitcnt vmcnt(8)
	ds_read_b64_tr_b16 v[98:99], v48 offset:4096
	ds_read_b64_tr_b16 v[100:101], v49 offset:4096
	ds_read_b64_tr_b16 v[104:105], v49 offset:6144
	ds_read_b64_tr_b16 v[102:103], v48 offset:6144
	v_add_u32_e32 v48, s78, v154
	v_add_u32_e32 v49, s78, v155
	ds_read_b64_tr_b16 v[106:107], v48 offset:4096
	ds_read_b64_tr_b16 v[108:109], v49 offset:4096
	ds_read_b64_tr_b16 v[112:113], v49 offset:6144
	ds_read_b64_tr_b16 v[110:111], v48 offset:6144
	s_waitcnt lgkmcnt(0)
	s_cmp_ge_i32 s3, s88
	s_cbranch_scc1 .LBB0_316
	s_addk_i32 s94, 0x60
	v_mad_i64_i32 v[48:49], s[84:85], s94, v218, v[142:143]
	s_mov_b32 m0, s78
	v_lshl_add_u64 v[50:51], v[48:49], 0, s[34:35]
	global_load_lds_dwordx4 v[50:51], off
	v_mad_i64_i32 v[50:51], s[84:85], s94, v218, v[144:145]
	v_lshl_add_u64 v[52:53], v[50:51], 0, s[96:97]
	s_add_i32 m0, s78, 0x400
	v_lshl_add_u64 v[48:49], v[48:49], 0, s[72:73]
	global_load_lds_dwordx4 v[52:53], off
	s_add_i32 m0, s78, 0x800
	s_nop 0
	global_load_lds_dwordx4 v[48:49], off
	v_lshl_add_u64 v[48:49], v[50:51], 0, s[6:7]
	s_add_i32 m0, s78, 0xc00
	v_mad_i64_i32 v[50:51], s[84:85], s94, v218, v[148:149]
	global_load_lds_dwordx4 v[48:49], off
	v_mad_i64_i32 v[48:49], s[84:85], s94, v218, v[146:147]
	s_add_i32 m0, s78, 0x1000
	v_lshl_add_u64 v[52:53], v[50:51], 0, s[26:27]
	global_load_lds_dwordx4 v[48:49], off
	s_add_i32 m0, s78, 0x1400
	v_lshl_add_u64 v[48:49], v[48:49], 0, s[28:29]
	global_load_lds_dwordx4 v[52:53], off
	s_add_i32 m0, s78, 0x1800
	s_nop 0
	global_load_lds_dwordx4 v[48:49], off
	v_lshl_add_u64 v[48:49], v[50:51], 0, s[30:31]
	s_add_i32 m0, s78, 0x1c00
	s_nop 0
	global_load_lds_dwordx4 v[48:49], off
